# v33b plus sc1 write-through on the 8 widened full-sector attention-output stores (published to W_out consumers on other XCDs)
# speedup vs baseline: 1.0124x; 1.0013x over previous
; __device__ __forceinline__ unsigned cvtpk(float lo, float hi) { f32x2_t v = {lo, hi}; bf16x2_t b = __builtin_convertvector(v, bf16x2_t); return __builtin_bit_cast(unsigned, b); }
; __device__ __forceinline__ void attn_phase(LAS unsigned char* lds, const bf16_t* Qb, const bf16_t* Kimg, const bf16_t* Vimg, bf16_t* AB, int bid, int G, int wave_k) {
;     ...
;         int lane_o = lane; asm volatile("" : "+v"(lane_o));
; #pragma unroll
;         for (int b = 0; b < 2; ++b) { const float lt = lrun[b] + __shfl_xor(lrun[b], 32), il = 1.f / lt;
;             bf16_t* orow = AB + (size_t)(qrow0 + 32 * b + (lane_o & 31)) * DM + h * VH + 4 * (lane_o >> 5);
; #pragma unroll
;             for (int g = 0; g < 4; ++g) {
;                 *(u32x2*)(orow + 8 * g) = (u32x2){cvtpk(o[b][0][4 * g] * il, o[b][0][4 * g + 1] * il), cvtpk(o[b][0][4 * g + 2] * il, o[b][0][4 * g + 3] * il)};
;                 *(u32x2*)(orow + 32 + 8 * g) = (u32x2){cvtpk(o[b][1][4 * g] * il, o[b][1][4 * g + 1] * il), cvtpk(o[b][1][4 * g + 2] * il, o[b][1][4 * g + 3] * il)}; } }
.LBB0_947:
	s_waitcnt lgkmcnt(0)
	s_barrier
	v_and_b32_e32 v66, 64, v229
	v_xor_b32_e32 v64, 32, v229
	v_add_u32_e32 v66, 64, v66
	v_mov_b32_e32 v65, v235
	v_cmp_lt_i32_e32 vcc, v64, v66
	s_lshl_b32 s0, s59, 7
	s_add_u32 s0, s40, s0
	v_cndmask_b32_e32 v64, v229, v64, vcc
	v_lshlrev_b32_e32 v69, 2, v64
	v_and_or_b32 v64, v65, 31, s60
	v_ashrrev_i32_e32 v65, 2, v65
	v_and_b32_e32 v66, -8, v65
	ds_bpermute_b32 v65, v69, v223
	s_addc_u32 s1, s41, 0
	v_ashrrev_i32_e32 v67, 31, v66
	v_lshl_add_u64 v[66:67], v[66:67], 1, s[0:1]
	s_add_i32 s26, s26, s27
	s_waitcnt lgkmcnt(0)
	v_add_f32_e32 v65, v223, v65
	v_div_scale_f32 v68, s[0:1], v65, v65, 1.0
	v_rcp_f32_e32 v70, v68
	s_cmpk_lt_i32 s26, 0x100
	v_fma_f32 v71, -v68, v70, 1.0
	v_fmac_f32_e32 v70, v71, v70
	v_div_scale_f32 v71, vcc, 1.0, v65, 1.0
	v_mul_f32_e32 v72, v71, v70
	v_fma_f32 v73, -v68, v72, v71
	v_fmac_f32_e32 v72, v73, v70
	v_fma_f32 v68, -v68, v72, v71
	v_div_fmas_f32 v68, v68, v70, v72
	v_div_fixup_f32 v68, v68, v65, 1.0
	v_ashrrev_i32_e32 v65, 31, v64
	v_lshlrev_b64 v[70:71], 11, v[64:65]
	v_lshl_add_u64 v[70:71], v[66:67], 0, v[70:71]
	ds_bpermute_b32 v74, v69, v222
	v_pk_mul_f32 v[32:33], v[32:33], v[68:69] op_sel_hi:[1,0]
	v_pk_mul_f32 v[34:35], v[34:35], v[68:69] op_sel_hi:[1,0]
	v_pk_mul_f32 v[36:37], v[36:37], v[68:69] op_sel_hi:[1,0]
	v_pk_mul_f32 v[38:39], v[38:39], v[68:69] op_sel_hi:[1,0]
	v_pk_mul_f32 v[40:41], v[40:41], v[68:69] op_sel_hi:[1,0]
	v_pk_mul_f32 v[42:43], v[42:43], v[68:69] op_sel_hi:[1,0]
	v_pk_mul_f32 v[44:45], v[44:45], v[68:69] op_sel_hi:[1,0]
	v_pk_mul_f32 v[46:47], v[46:47], v[68:69] op_sel_hi:[1,0]
	v_pk_mul_f32 v[48:49], v[48:49], v[68:69] op_sel_hi:[1,0]
	v_pk_mul_f32 v[50:51], v[50:51], v[68:69] op_sel_hi:[1,0]
	v_pk_mul_f32 v[52:53], v[52:53], v[68:69] op_sel_hi:[1,0]
	v_pk_mul_f32 v[54:55], v[54:55], v[68:69] op_sel_hi:[1,0]
	v_pk_mul_f32 v[56:57], v[56:57], v[68:69] op_sel_hi:[1,0]
	v_pk_mul_f32 v[58:59], v[58:59], v[68:69] op_sel_hi:[1,0]
	v_pk_mul_f32 v[60:61], v[60:61], v[68:69] op_sel_hi:[1,0]
	v_pk_mul_f32 v[62:63], v[62:63], v[68:69] op_sel_hi:[1,0]
	v_cvt_pk_bf16_f32 v32, v32, v33
	v_cvt_pk_bf16_f32 v33, v34, v35
	v_cvt_pk_bf16_f32 v34, v36, v37
	v_cvt_pk_bf16_f32 v35, v38, v39
	v_cvt_pk_bf16_f32 v40, v40, v41
	v_cvt_pk_bf16_f32 v41, v42, v43
	v_cvt_pk_bf16_f32 v42, v44, v45
	v_cvt_pk_bf16_f32 v43, v46, v47
	v_cvt_pk_bf16_f32 v48, v48, v49
	v_cvt_pk_bf16_f32 v49, v50, v51
	v_cvt_pk_bf16_f32 v50, v52, v53
	v_cvt_pk_bf16_f32 v51, v54, v55
	v_cvt_pk_bf16_f32 v56, v56, v57
	v_cvt_pk_bf16_f32 v57, v58, v59
	v_cvt_pk_bf16_f32 v58, v60, v61
	v_cvt_pk_bf16_f32 v59, v62, v63
	v_permlane32_swap_b32_e32 v32, v34
	v_permlane32_swap_b32_e32 v33, v35
	v_permlane32_swap_b32_e32 v40, v42
	v_permlane32_swap_b32_e32 v41, v43
	v_permlane32_swap_b32_e32 v48, v50
	v_permlane32_swap_b32_e32 v49, v51
	v_permlane32_swap_b32_e32 v56, v58
	v_permlane32_swap_b32_e32 v57, v59
	global_store_dwordx4 v[70:71], v[32:35], off offset:64 sc1
	global_store_dwordx4 v[70:71], v[40:43], off offset:96 sc1
	global_store_dwordx4 v[70:71], v[48:51], off sc1
	global_store_dwordx4 v[70:71], v[56:59], off offset:32 sc1
	s_waitcnt lgkmcnt(0)
	v_add_f32_e32 v74, v222, v74
	v_div_scale_f32 v75, s[0:1], v74, v74, 1.0
	v_rcp_f32_e32 v76, v75
	s_nop 0
	v_fma_f32 v77, -v75, v76, 1.0
	v_fmac_f32_e32 v76, v77, v76
	v_div_scale_f32 v77, vcc, 1.0, v74, 1.0
	v_mul_f32_e32 v78, v77, v76
	v_fma_f32 v79, -v75, v78, v77
	v_fmac_f32_e32 v78, v79, v76
	v_fma_f32 v75, -v75, v78, v77
	v_div_fmas_f32 v75, v75, v76, v78
	v_or_b32_e32 v76, 32, v64
	v_div_fixup_f32 v74, v75, v74, 1.0
	v_ashrrev_i32_e32 v77, 31, v76
	v_lshlrev_b64 v[76:77], 11, v[76:77]
	v_lshl_add_u64 v[76:77], v[66:67], 0, v[76:77]
	v_pk_mul_f32 v[0:1], v[0:1], v[74:75] op_sel_hi:[1,0]
	v_pk_mul_f32 v[2:3], v[2:3], v[74:75] op_sel_hi:[1,0]
	v_pk_mul_f32 v[4:5], v[4:5], v[74:75] op_sel_hi:[1,0]
	v_pk_mul_f32 v[6:7], v[6:7], v[74:75] op_sel_hi:[1,0]
	v_pk_mul_f32 v[8:9], v[8:9], v[74:75] op_sel_hi:[1,0]
	v_pk_mul_f32 v[10:11], v[10:11], v[74:75] op_sel_hi:[1,0]
	v_pk_mul_f32 v[12:13], v[12:13], v[74:75] op_sel_hi:[1,0]
	v_pk_mul_f32 v[14:15], v[14:15], v[74:75] op_sel_hi:[1,0]
	v_pk_mul_f32 v[16:17], v[16:17], v[74:75] op_sel_hi:[1,0]
	v_pk_mul_f32 v[18:19], v[18:19], v[74:75] op_sel_hi:[1,0]
	v_pk_mul_f32 v[20:21], v[20:21], v[74:75] op_sel_hi:[1,0]
	v_pk_mul_f32 v[22:23], v[22:23], v[74:75] op_sel_hi:[1,0]
	v_pk_mul_f32 v[24:25], v[24:25], v[74:75] op_sel_hi:[1,0]
	v_pk_mul_f32 v[26:27], v[26:27], v[74:75] op_sel_hi:[1,0]
	v_pk_mul_f32 v[28:29], v[28:29], v[74:75] op_sel_hi:[1,0]
	v_pk_mul_f32 v[30:31], v[30:31], v[74:75] op_sel_hi:[1,0]
	v_cvt_pk_bf16_f32 v0, v0, v1
	v_cvt_pk_bf16_f32 v1, v2, v3
	v_cvt_pk_bf16_f32 v2, v4, v5
	v_cvt_pk_bf16_f32 v3, v6, v7
	v_cvt_pk_bf16_f32 v8, v8, v9
	v_cvt_pk_bf16_f32 v9, v10, v11
	v_cvt_pk_bf16_f32 v10, v12, v13
	v_cvt_pk_bf16_f32 v11, v14, v15
	v_cvt_pk_bf16_f32 v16, v16, v17
	v_cvt_pk_bf16_f32 v17, v18, v19
	v_cvt_pk_bf16_f32 v18, v20, v21
	v_cvt_pk_bf16_f32 v19, v22, v23
	v_cvt_pk_bf16_f32 v24, v24, v25
	v_cvt_pk_bf16_f32 v25, v26, v27
	v_cvt_pk_bf16_f32 v26, v28, v29
	v_cvt_pk_bf16_f32 v27, v30, v31
	v_permlane32_swap_b32_e32 v0, v2
	v_permlane32_swap_b32_e32 v1, v3
	v_permlane32_swap_b32_e32 v8, v10
	v_permlane32_swap_b32_e32 v9, v11
	v_permlane32_swap_b32_e32 v16, v18
	v_permlane32_swap_b32_e32 v17, v19
	v_permlane32_swap_b32_e32 v24, v26
	v_permlane32_swap_b32_e32 v25, v27
	global_store_dwordx4 v[76:77], v[0:3], off offset:64 sc1
	global_store_dwordx4 v[76:77], v[8:11], off offset:96 sc1
	global_store_dwordx4 v[76:77], v[16:19], off sc1
	global_store_dwordx4 v[76:77], v[24:27], off offset:32 sc1
	s_cbranch_scc0 .LBB0_985
